# LN row loop: gain/bias vectors hoisted out of the row loop (were reloaded per chunk behind vmcnt(0)), conservative vmcnt(5..2) before the row reduction removed so the next row's prefetch overlaps
# speedup vs baseline: 1.0028x; 1.0028x over previous
; DI int opaque_tid() { int t = threadIdx.x; asm volatile("" : "+v"(t)); return t; }
; DI void ln_rows(const Params& p, int l) {
;   const int tid = opaque_tid(), lane = tid & 63, w = tid >> 6;
;   const float* gg = l < 0 ? p.ln0_g : p.ln_g + l * DM;
;   const float* bb = l < 0 ? p.ln0_b : p.ln_b + l * DM;
;   const int stride = gridDim.x * 8;
;   auto loadrow = [&](int row, f32x4* dst) {
;     if (l < 0) {
;       const int b = row / PP, t = row - b * PP;
;       const float* src = nullptr;
;       if (t >= 128 && t < PV) src = p.x + ((size_t)b * SEQ + (t - 128)) * DM;
;       else if (t >= LEAD && t < 128) src = p.meta + (size_t)(t - LEAD) * DM;
; #pragma unroll
;       for (int j = 0; j < 4; ++j) {
;         if (src) dst[j] = *(const f32x4*)(src + lane * 4 + 256 * j);
;         else { dst[j][0] = 0.f; dst[j][1] = 0.f; dst[j][2] = 0.f; dst[j][3] = 0.f; }
;       }
;     } else {
; #pragma unroll
;       for (int j = 0; j < 4; ++j) {
;         dst[j] = *(const f32x4*)(p.R + (size_t)row * DM + lane * 4 + 256 * j);
;         if (row >= 16384) {
; #pragma unroll
;           for (int q = 0; q < 3; ++q) dst[j] += *(const f32x4*)(p.Y1 + ((size_t)q * 512 + (row - 16384)) * DM + lane * 4 + 256 * j);
;         }
;       }
;     }
;   };
;   f32x4 v[4], vn[4];
;   int row = blockIdx.x * 8 + w;
;   if (row < MT) loadrow(row, v);
;   for (; row < MT; row += stride) {
;     const int b = row / PP, t = row - b * PP;
;     if (row + stride < MT) loadrow(row + stride, vn);
;     ...
;       const int c = lane * 4 + 256 * j;
;       f32x4 g4 = *(const f32x4*)(gg + c), b4 = *(const f32x4*)(bb + c);
.LBB0_2815:
	s_or_b64 exec, exec, s[4:5]
	s_and_saveexec_b64 s[4:5], s[0:1]
	s_cbranch_execz .LBB0_2852
	s_lshl_b32 s60, s38, 10
	s_lshl_b64 s[0:1], s[60:61], 2
	v_readlane_b32 s18, v241, 59
	v_readlane_b32 s19, v241, 60
	s_add_u32 s2, s18, s0
	v_readlane_b32 s20, v241, 61
	s_addc_u32 s3, s19, s1
	v_readlane_b32 s21, v241, 62
	s_add_u32 s0, s20, s0
	s_addc_u32 s1, s21, s1
	v_mov_b32_e32 v15, v3
	v_lshl_add_u64 v[38:39], s[0:1], 0, v[14:15]
	v_readlane_b32 s8, v241, 40
	v_readlane_b32 s0, v238, 19
	v_readlane_b32 s22, v240, 15
	v_readlane_b32 s23, v240, 16
	v_readlane_b32 s9, v241, 41
	v_add_u32_e32 v58, s0, v28
	v_readlane_b32 s0, v238, 20
	v_lshl_add_u64 v[36:37], s[2:3], 0, v[14:15]
	v_lshl_add_u64 v[40:41], s[22:23], 0, v[14:15]
	v_lshl_add_u64 v[42:43], s[8:9], 0, v[14:15]
	v_add_u32_e32 v14, s0, v28
	v_ashrrev_i32_e32 v15, 31, v14
	v_lshlrev_b64 v[44:45], 12, v[14:15]
	v_lshlrev_b64 v[14:15], 11, v[12:13]
	v_readlane_b32 s0, v238, 23
	v_lshl_or_b32 v14, v1, 3, v14
	v_readlane_b32 s1, v238, 24
	v_lshlrev_b64 v[48:49], 12, v[12:13]
	v_mov_b32_e32 v12, 0
	s_mov_b32 s60, 0x20000
	v_readlane_b32 s18, v238, 43
	v_lshl_add_u64 v[46:47], s[0:1], 0, v[14:15]
	s_mov_b64 s[6:7], 0
	v_mov_b32_e32 v13, v12
	v_mov_b32_e32 v14, v12
	v_mov_b32_e32 v15, v12
	v_mov_b32_e32 v20, v12
	v_mov_b32_e32 v21, v12
	v_mov_b32_e32 v22, v12
	v_mov_b32_e32 v23, v12
	v_mov_b32_e32 v28, v12
	v_mov_b32_e32 v29, v12
	v_mov_b32_e32 v30, v12
	v_mov_b32_e32 v31, v12
	v_mov_b32_e32 v32, v12
	v_mov_b32_e32 v33, v12
	v_mov_b32_e32 v34, v12
	v_mov_b32_e32 v35, v12
	v_readlane_b32 s13, v241, 45
	global_load_dwordx4 v[96:99], v[36:37], off
	global_load_dwordx4 v[112:115], v[38:39], off
	global_load_dwordx4 v[100:103], v[36:37], off offset:1024
	global_load_dwordx4 v[116:119], v[38:39], off offset:1024
	global_load_dwordx4 v[104:107], v[36:37], off offset:2048
	global_load_dwordx4 v[120:123], v[38:39], off offset:2048
	global_load_dwordx4 v[108:111], v[36:37], off offset:3072
	global_load_dwordx4 v[124:127], v[38:39], off offset:3072
	s_waitcnt vmcnt(0)
	s_branch .LBB0_2819

; DI void ln_rows(const Params& p, int l) {
;     ...
;   for (; row < MT; row += stride) {
;     const int b = row / PP, t = row - b * PP;
;     if (row + stride < MT) loadrow(row + stride, vn);
;     ...
; #pragma unroll
;     for (int j = 0; j < 4; ++j) v[j] = vn[j];
.LBB0_2818:
	s_waitcnt vmcnt(0)
	v_readlane_b32 s0, v238, 21
	v_readlane_b32 s1, v238, 22
	v_mov_b32_e32 v58, v1
	v_mov_b32_e32 v4, v12
	v_lshl_add_u64 v[40:41], v[40:41], 0, s[0:1]
	v_readlane_b32 s0, v238, 33
	v_readlane_b32 s1, v238, 34
	v_mov_b32_e32 v5, v13
	v_mov_b32_e32 v6, v14
	v_lshl_add_u64 v[46:47], v[46:47], 0, s[0:1]
	v_mov_b32_e32 v7, v15
	v_mov_b32_e32 v8, v20
	v_mov_b32_e32 v9, v21
	v_mov_b32_e32 v10, v22
	v_mov_b32_e32 v11, v23
	v_mov_b32_e32 v16, v28
	v_mov_b32_e32 v17, v29
	v_mov_b32_e32 v18, v30
	v_mov_b32_e32 v19, v31
	v_mov_b32_e32 v24, v32
	v_mov_b32_e32 v25, v33
	v_mov_b32_e32 v26, v34
	v_mov_b32_e32 v27, v35
	s_andn2_b64 exec, exec, s[6:7]
	s_cbranch_execz .LBB0_2852

; DI unsigned pk2(float a, float b) { f32x2 v = {a, b}; return __builtin_bit_cast(unsigned, __builtin_convertvector(v, bf2_t)); }
; DI void ln_rows(const Params& p, int l) {
;     ...
;     float s = 0.f;
; #pragma unroll
;     for (int j = 0; j < 4; ++j) s += v[j][0] + v[j][1] + v[j][2] + v[j][3];
;     const float mu = wsum(s) * (1.f / DM);
;     float q = 0.f;
; #pragma unroll
;     for (int j = 0; j < 4; ++j)
; #pragma unroll
;       for (int e = 0; e < 4; ++e) { float d = v[j][e] - mu; q += d * d; }
;     const float rstd = rsqrtf(wsum(q) * (1.f / DM) + 1e-5f);
; #pragma unroll
;     for (int j = 0; j < 4; ++j) {
;       const int c = lane * 4 + 256 * j;
;       f32x4 g4 = *(const f32x4*)(gg + c), b4 = *(const f32x4*)(bb + c);
;       f32x4 y;
; #pragma unroll
;       for (int e = 0; e < 4; ++e) y[e] = (v[j][e] - mu) * rstd * g4[e] + b4[e];
;       if (l == 3) {
;         if (t >= 128 && t < PV) *(f32x4*)(p.out + ((size_t)b * SEQ + (t - 128)) * DM + c) = y;
;       } else {
;         *(f32x4*)(p.R + (size_t)row * DM + c) = y;
;         u32x2 yb = {pk2(y[0], y[1]), pk2(y[2], y[3])};
;         *(u32x2*)(p.Xb + (size_t)row * DM + c) = yb;
.LBB0_2827:
	s_or_b64 exec, exec, s[8:9]
	s_and_b64 s[0:1], exec, s[0:1]
	s_or_b64 s[6:7], s[0:1], s[6:7]
	v_add_u32_e32 v2, 0x80, v58
	s_mov_b32 s0, 0x3e0f83e1
	v_mul_hi_i32 v2, v2, s0
	v_lshrrev_b32_e32 v59, 31, v2
	v_ashrrev_i32_e32 v76, 11, v2
	v_add_f32_e32 v2, v4, v5
	v_add_f32_e32 v2, v6, v2
	v_add_f32_e32 v50, v8, v9
	v_add_f32_e32 v2, v7, v2
	v_add_f32_e32 v50, v10, v50
	v_add_f32_e32 v2, 0, v2
	v_add_f32_e32 v50, v11, v50
	v_add_f32_e32 v2, v50, v2
	v_add_f32_e32 v50, v16, v17
	v_add_f32_e32 v50, v18, v50
	v_add_f32_e32 v50, v19, v50
	v_add_f32_e32 v2, v50, v2
	v_add_f32_e32 v50, v24, v25
	v_add_f32_e32 v50, v26, v50
	v_add_f32_e32 v50, v27, v50
	v_add_f32_e32 v2, v50, v2
	s_mov_b32 s0, 0x800000
	v_readlane_b32 s8, v238, 52
	v_add_f32_dpp v2, v2, v2 quad_perm:[1,0,3,2] row_mask:0xf bank_mask:0xf bound_ctrl:1
	v_readlane_b32 s9, v238, 53
	s_mov_b64 s[2:3], -1
	v_add_f32_dpp v2, v2, v2 quad_perm:[2,3,0,1] row_mask:0xf bank_mask:0xf bound_ctrl:1
	s_nop 1
	v_add_f32_dpp v2, v2, v2 row_half_mirror row_mask:0xf bank_mask:0xf bound_ctrl:1
	s_nop 1
	v_add_f32_dpp v2, v2, v2 row_mirror row_mask:0xf bank_mask:0xf bound_ctrl:1
	v_mov_b32_e32 v50, v2
	s_nop 1
	v_permlane16_swap_b32_e32 v2, v50
	v_add_f32_e32 v2, v2, v50
	v_mov_b32_e32 v50, v2
	s_nop 1
	v_permlane32_swap_b32_e32 v2, v50
	v_add_f32_e32 v2, v2, v50
	v_mul_f32_e32 v2, 0x3a800000, v2
	v_pk_add_f32 v[4:5], v[4:5], v[2:3] op_sel_hi:[1,0] neg_lo:[0,1] neg_hi:[0,1]
	v_pk_add_f32 v[6:7], v[6:7], v[2:3] op_sel_hi:[1,0] neg_lo:[0,1] neg_hi:[0,1]
	v_pk_mul_f32 v[74:75], v[4:5], v[4:5]
	v_pk_add_f32 v[54:55], v[8:9], v[2:3] op_sel_hi:[1,0] neg_lo:[0,1] neg_hi:[0,1]
	v_pk_add_f32 v[56:57], v[10:11], v[2:3] op_sel_hi:[1,0] neg_lo:[0,1] neg_hi:[0,1]
	v_pk_add_f32 v[50:51], v[16:17], v[2:3] op_sel_hi:[1,0] neg_lo:[0,1] neg_hi:[0,1]
	v_pk_add_f32 v[52:53], v[18:19], v[2:3] op_sel_hi:[1,0] neg_lo:[0,1] neg_hi:[0,1]
	v_pk_add_f32 v[8:9], v[24:25], v[2:3] op_sel_hi:[1,0] neg_lo:[0,1] neg_hi:[0,1]
	v_pk_add_f32 v[10:11], v[26:27], v[2:3] op_sel_hi:[1,0] neg_lo:[0,1] neg_hi:[0,1]
	v_pk_mul_f32 v[72:73], v[6:7], v[6:7]
	v_add_f32_e32 v2, v74, v75
	v_add_f32_e32 v2, v72, v2
	v_pk_mul_f32 v[68:69], v[54:55], v[54:55]
	v_add_f32_e32 v2, v73, v2
	v_add_f32_e32 v2, v68, v2
	v_pk_mul_f32 v[70:71], v[56:57], v[56:57]
	v_add_f32_e32 v2, v69, v2
	v_add_f32_e32 v2, v70, v2
	v_pk_mul_f32 v[16:17], v[50:51], v[50:51]
	v_add_f32_e32 v2, v71, v2
	v_add_f32_e32 v2, v16, v2
	v_pk_mul_f32 v[18:19], v[52:53], v[52:53]
	v_add_f32_e32 v2, v17, v2
	v_add_f32_e32 v2, v18, v2
	v_pk_mul_f32 v[24:25], v[8:9], v[8:9]
	v_add_f32_e32 v2, v19, v2
	v_add_f32_e32 v2, v24, v2
	v_pk_mul_f32 v[26:27], v[10:11], v[10:11]
	v_add_f32_e32 v2, v25, v2
	v_add_f32_e32 v2, v26, v2
	v_add_f32_e32 v2, v27, v2
	v_lshl_add_u64 v[24:25], v[40:41], 0, v[48:49]
	s_nop 0
	v_add_f32_dpp v2, v2, v2 quad_perm:[1,0,3,2] row_mask:0xf bank_mask:0xf bound_ctrl:1
	s_nop 1
	v_add_f32_dpp v2, v2, v2 quad_perm:[2,3,0,1] row_mask:0xf bank_mask:0xf bound_ctrl:1
	s_nop 1
	v_add_f32_dpp v2, v2, v2 row_half_mirror row_mask:0xf bank_mask:0xf bound_ctrl:1
	s_nop 1
	v_add_f32_dpp v2, v2, v2 row_mirror row_mask:0xf bank_mask:0xf bound_ctrl:1
	v_mov_b32_e32 v16, v2
	s_nop 1
	v_permlane16_swap_b32_e32 v2, v16
	v_add_f32_e32 v2, v2, v16
	v_mov_b32_e32 v16, v2
	s_nop 1
	v_permlane32_swap_b32_e32 v2, v16
	v_add_f32_e32 v2, v2, v16
	v_fmamk_f32 v2, v2, 0x3a800000, v196
	v_mul_f32_e32 v16, 0x4b800000, v2
	v_cmp_gt_f32_e32 vcc, s0, v2
	s_movk_i32 s0, 0xdf00
	s_nop 0
	v_cndmask_b32_e32 v2, v2, v16, vcc
	v_rsq_f32_e32 v17, v2
	v_add_u32_e32 v16, v76, v59
	v_mad_i32_i24 v2, v16, s0, v58
	s_movk_i32 s0, 0x2000
	v_mul_f32_e32 v18, 0x45800000, v17
	v_cndmask_b32_e32 v18, v17, v18, vcc
	v_pk_mul_f32 v[4:5], v[4:5], v[18:19] op_sel_hi:[1,0]
	v_pk_mul_f32 v[6:7], v[6:7], v[18:19] op_sel_hi:[1,0]
	v_cmp_gt_u32_e64 s[0:1], s0, v2
	v_pk_fma_f32 v[4:5], v[96:97], v[4:5], v[112:113]
	v_pk_fma_f32 v[6:7], v[98:99], v[6:7], v[114:115]
	s_and_b64 vcc, exec, s[8:9]
	s_cbranch_vccz .LBB0_2829
	v_cvt_pk_bf16_f32 v26, v4, v5
	v_cvt_pk_bf16_f32 v27, v6, v7
	global_store_dwordx4 v[24:25], v[4:7], off
	global_store_dwordx2 v[46:47], v[26:27], off offset:-1024
	s_mov_b64 s[2:3], 0

; DI unsigned pk2(float a, float b) { f32x2 v = {a, b}; return __builtin_bit_cast(unsigned, __builtin_convertvector(v, bf2_t)); }
; DI void ln_rows(const Params& p, int l) {
;     ...
;     for (int j = 0; j < 4; ++j) {
;       const int c = lane * 4 + 256 * j;
;       f32x4 g4 = *(const f32x4*)(gg + c), b4 = *(const f32x4*)(bb + c);
;       f32x4 y;
; #pragma unroll
;       for (int e = 0; e < 4; ++e) y[e] = (v[j][e] - mu) * rstd * g4[e] + b4[e];
;       if (l == 3) {
;         if (t >= 128 && t < PV) *(f32x4*)(p.out + ((size_t)b * SEQ + (t - 128)) * DM + c) = y;
;       } else {
;         *(f32x4*)(p.R + (size_t)row * DM + c) = y;
;         u32x2 yb = {pk2(y[0], y[1]), pk2(y[2], y[3])};
;         *(u32x2*)(p.Xb + (size_t)row * DM + c) = yb;
;       }
.LBB0_2833:
	v_mov_b32_e32 v19, v18
	v_pk_mul_f32 v[26:27], v[54:55], v[18:19]
	v_pk_mul_f32 v[54:55], v[56:57], v[18:19]
	s_and_b64 vcc, exec, s[62:63]
	s_mov_b64 s[2:3], -1
	v_pk_fma_f32 v[4:5], v[26:27], v[100:101], v[116:117]
	v_pk_fma_f32 v[6:7], v[54:55], v[102:103], v[118:119]
	s_cbranch_vccnz .LBB0_2835
	v_cvt_pk_bf16_f32 v26, v4, v5
	v_cvt_pk_bf16_f32 v27, v6, v7
	s_mov_b64 s[2:3], 0
	global_store_dwordx4 v[24:25], v[4:7], off offset:1024
	global_store_dwordx2 v[46:47], v[26:27], off offset:-512

; DI unsigned pk2(float a, float b) { f32x2 v = {a, b}; return __builtin_bit_cast(unsigned, __builtin_convertvector(v, bf2_t)); }
; DI void ln_rows(const Params& p, int l) {
;     ...
;     for (int j = 0; j < 4; ++j) {
;       const int c = lane * 4 + 256 * j;
;       f32x4 g4 = *(const f32x4*)(gg + c), b4 = *(const f32x4*)(bb + c);
;       f32x4 y;
; #pragma unroll
;       for (int e = 0; e < 4; ++e) y[e] = (v[j][e] - mu) * rstd * g4[e] + b4[e];
;       if (l == 3) {
;         if (t >= 128 && t < PV) *(f32x4*)(p.out + ((size_t)b * SEQ + (t - 128)) * DM + c) = y;
;       } else {
;         *(f32x4*)(p.R + (size_t)row * DM + c) = y;
;         u32x2 yb = {pk2(y[0], y[1]), pk2(y[2], y[3])};
;         *(u32x2*)(p.Xb + (size_t)row * DM + c) = yb;
;       }
.LBB0_2839:
	v_pk_mul_f32 v[26:27], v[50:51], v[18:19]
	v_pk_mul_f32 v[50:51], v[52:53], v[18:19]
	s_and_b64 vcc, exec, s[62:63]
	s_mov_b64 s[2:3], -1
	v_pk_fma_f32 v[4:5], v[26:27], v[104:105], v[120:121]
	v_pk_fma_f32 v[6:7], v[50:51], v[106:107], v[122:123]
	s_cbranch_vccnz .LBB0_2841
	v_cvt_pk_bf16_f32 v26, v4, v5
	v_cvt_pk_bf16_f32 v27, v6, v7
	s_mov_b64 s[2:3], 0
	global_store_dwordx4 v[24:25], v[4:7], off offset:2048
	global_store_dwordx2 v[46:47], v[26:27], off

; DI unsigned pk2(float a, float b) { f32x2 v = {a, b}; return __builtin_bit_cast(unsigned, __builtin_convertvector(v, bf2_t)); }
; DI void ln_rows(const Params& p, int l) {
;     ...
;     for (int j = 0; j < 4; ++j) {
;       const int c = lane * 4 + 256 * j;
;       f32x4 g4 = *(const f32x4*)(gg + c), b4 = *(const f32x4*)(bb + c);
;       f32x4 y;
; #pragma unroll
;       for (int e = 0; e < 4; ++e) y[e] = (v[j][e] - mu) * rstd * g4[e] + b4[e];
;       if (l == 3) {
;         if (t >= 128 && t < PV) *(f32x4*)(p.out + ((size_t)b * SEQ + (t - 128)) * DM + c) = y;
;       } else {
;         *(f32x4*)(p.R + (size_t)row * DM + c) = y;
;         u32x2 yb = {pk2(y[0], y[1]), pk2(y[2], y[3])};
;         *(u32x2*)(p.Xb + (size_t)row * DM + c) = yb;
;       }
.LBB0_2845:
	v_pk_mul_f32 v[8:9], v[8:9], v[18:19]
	v_pk_mul_f32 v[10:11], v[10:11], v[18:19]
	s_and_b64 vcc, exec, s[62:63]
	s_mov_b64 s[2:3], -1
	v_pk_fma_f32 v[4:5], v[8:9], v[108:109], v[124:125]
	v_pk_fma_f32 v[6:7], v[10:11], v[110:111], v[126:127]
	s_cbranch_vccnz .LBB0_2847
	v_cvt_pk_bf16_f32 v8, v4, v5
	v_cvt_pk_bf16_f32 v9, v6, v7
	s_mov_b64 s[2:3], 0
	global_store_dwordx4 v[24:25], v[4:7], off offset:3072
	global_store_dwordx2 v[46:47], v[8:9], off offset:512
